# up1/up2 epilogue store addresses: two bases per unit + immediate offsets instead of 5-6 VALU address ops per store (84 fewer VALU per unit)
# speedup vs baseline: 1.0008x; 1.0008x over previous
; __device__ __forceinline__ unsigned cvt_pk_bf16(float lo, float hi) { unsigned r; asm volatile("v_cvt_pk_bf16_f32 %0, %1, %2" : "=v"(r) : "v"(lo), "v"(hi)); return r; }
; __device__ __forceinline__ float silu_mul(float g, float u) { return g * __builtin_amdgcn_rcpf(1.0f + __builtin_amdgcn_exp2f(-1.4426950408889634f * g)) * u; }
;     __device__ __forceinline__ void operator()(const f32x4 (&acc)[2][2][4][2], const Unit& u, int wr, int wc, int fr, int fq) const {
;         const int row0 = u.pm * BM + wr * 64 + fr, j0 = u.pn * HALF + wc * 32 + 8 * fq;
;         float rs[2][4];
; #pragma unroll
;         for (int ai = 0; ai < 2; ++ai)
; #pragma unroll
;             for (int m = 0; m < 4; ++m) rs[ai][m] = ss[row0 + ai * HALF + m * 16];
;         __builtin_amdgcn_sched_barrier(0);
; #pragma unroll
;         for (int ai = 0; ai < 2; ++ai)
; #pragma unroll
;             for (int m = 0; m < 4; ++m) {
;                 const int row = row0 + ai * HALF + m * 16;
;                 const float r = __builtin_amdgcn_rsqf(rs[ai][m] * (1.0f / DM) + EPSN);
;                 const f32x4 g0 = acc[ai][0][m][0] * r, g1 = acc[ai][0][m][1] * r, u0 = acc[ai][1][m][0] * r, u1 = acc[ai][1][m][1] * r;
;                 u32x4 w;
;                 w.x = cvt_pk_bf16(silu_mul(g0[0], u0[0]), silu_mul(g0[1], u0[1])); w.y = cvt_pk_bf16(silu_mul(g0[2], u0[2]), silu_mul(g0[3], u0[3]));
;                 w.z = cvt_pk_bf16(silu_mul(g1[0], u1[0]), silu_mul(g1[1], u1[1])); w.w = cvt_pk_bf16(silu_mul(g1[2], u1[2]), silu_mul(g1[3], u1[3]));
;                 *(u32x4*)(act + (((size_t)u.pm * (DFF / 64) + (u.pn * 2 + (wc >> 1))) * 256 + (row - u.pm * BM)) * 64 + (wc & 1) * 32 + 8 * fq) = w;
.LBB0_280:
	s_lshl_b32 s27, s38, 8
	v_add_u32_e32 v136, s27, v128
	v_or_b32_e32 v140, 16, v136
	v_ashrrev_i32_e32 v137, 31, v136
	v_ashrrev_i32_e32 v141, 31, v140
	v_lshl_add_u64 v[148:149], v[136:137], 2, s[18:19]
	v_lshl_add_u64 v[138:139], v[140:141], 2, s[18:19]
	global_load_dword v150, v[148:149], off
	global_load_dword v152, v[138:139], off
	v_or_b32_e32 v138, 32, v136
	v_ashrrev_i32_e32 v139, 31, v138
	v_or_b32_e32 v136, 48, v136
	v_lshl_add_u64 v[146:147], v[138:139], 2, s[18:19]
	v_ashrrev_i32_e32 v137, 31, v136
	global_load_dword v153, v[146:147], off
	v_lshl_add_u64 v[146:147], v[136:137], 2, s[18:19]
	global_load_dword v147, v[146:147], off
	s_nop 0
	global_load_dword v146, v[148:149], off offset:512
	global_load_dword v141, v[148:149], off offset:576
	global_load_dword v139, v[148:149], off offset:640
	global_load_dword v137, v[148:149], off offset:704
	s_waitcnt vmcnt(0)
	s_mov_b32 s98, 0x1000
	s_mov_b32 s99, 0
	s_mov_b32 s100, 0xbfb8aa3b
	s_mov_b32 s101, 0xbfb8aa3b
	v_fmamk_f32 v148, v150, 0x3a000000, v145
	v_rsq_f32_e32 v148, v148
	s_lshl_b32 s39, s39, 1
	s_or_b32 s39, s39, s48
	s_mul_hi_i32 s29, s38, 0x56
	v_pk_mul_f32 v[124:125], v[124:125], v[148:149] op_sel_hi:[1,0]
	v_pk_mul_f32 v[150:151], v[114:115], v[148:149] op_sel_hi:[1,0]
	v_pk_mul_f32 v[114:115], v[112:113], v[148:149] op_sel_hi:[1,0]
	v_pk_mul_f32 v[116:117], v[116:117], v[148:149] op_sel_hi:[1,0]
	v_pk_mul_f32 v[126:127], v[126:127], v[148:149] op_sel_hi:[1,0]
	v_pk_mul_f32 v[118:119], v[118:119], v[148:149] op_sel_hi:[1,0]
	v_pk_mul_f32 v[120:121], v[120:121], v[148:149] op_sel_hi:[1,0]
	v_pk_mul_f32 v[122:123], v[122:123], v[148:149] op_sel_hi:[1,0]
	v_pk_mul_f32 v[154:155], v[124:125], s[100:101]
	v_pk_mul_f32 v[156:157], v[126:127], s[100:101]
	v_exp_f32_e32 v154, v154
	v_exp_f32_e32 v155, v155
	v_exp_f32_e32 v156, v156
	v_exp_f32_e32 v157, v157
	v_pk_add_f32 v[154:155], v[154:155], 1.0 op_sel_hi:[1,0]
	v_pk_add_f32 v[156:157], v[156:157], 1.0 op_sel_hi:[1,0]
	v_rcp_f32_e32 v154, v154
	v_rcp_f32_e32 v155, v155
	v_rcp_f32_e32 v156, v156
	v_rcp_f32_e32 v157, v157
	v_pk_mul_f32 v[154:155], v[124:125], v[154:155]
	v_pk_mul_f32 v[156:157], v[126:127], v[156:157]
	v_pk_mul_f32 v[154:155], v[116:117], v[154:155]
	v_pk_mul_f32 v[156:157], v[118:119], v[156:157]
	v_pk_mul_f32 v[158:159], v[120:121], s[100:101]
	v_pk_mul_f32 v[160:161], v[122:123], s[100:101]
	v_exp_f32_e32 v158, v158
	v_exp_f32_e32 v159, v159
	v_exp_f32_e32 v160, v160
	v_exp_f32_e32 v161, v161
	v_pk_add_f32 v[158:159], v[158:159], 1.0 op_sel_hi:[1,0]
	v_pk_add_f32 v[160:161], v[160:161], 1.0 op_sel_hi:[1,0]
	v_rcp_f32_e32 v158, v158
	v_rcp_f32_e32 v159, v159
	v_rcp_f32_e32 v160, v160
	v_rcp_f32_e32 v161, v161
	v_pk_mul_f32 v[158:159], v[120:121], v[158:159]
	v_pk_mul_f32 v[160:161], v[122:123], v[160:161]
	v_pk_mul_f32 v[158:159], v[114:115], v[158:159]
	v_pk_mul_f32 v[160:161], v[150:151], v[160:161]
	v_cvt_pk_bf16_f32 v112, v154, v155
	v_cvt_pk_bf16_f32 v113, v156, v157
	v_cvt_pk_bf16_f32 v114, v158, v159
	v_cvt_pk_bf16_f32 v115, v160, v161
	s_mulk_i32 s38, 0x56
	s_ashr_i32 s40, s39, 31
	s_add_u32 s38, s38, s39
	s_addc_u32 s39, s29, s40
	s_lshl_b64 s[38:39], s[38:39], 15
	s_add_u32 s38, s4, s38
	s_addc_u32 s39, s5, s39
	s_nop 0
	s_nop 0
	v_lshl_add_u64 v[116:117], s[38:39], 0, v[130:131]
	v_lshl_add_u64 v[116:117], v[116:117], 0, s[22:23]
	v_lshl_add_u64 v[116:117], v[116:117], 0, v[200:201]
	v_lshl_add_u64 v[164:165], v[116:117], 0, s[98:99]
	v_lshl_add_u64 v[166:167], s[98:99], 2, v[164:165]
	global_store_dwordx4 v[116:117], v[112:115], off
	s_nop 1
	v_fmamk_f32 v112, v152, 0x3a000000, v145
	v_rsq_f32_e32 v112, v112
	s_nop 0
	v_pk_mul_f32 v[108:109], v[108:109], v[112:113] op_sel_hi:[1,0]
	v_pk_mul_f32 v[114:115], v[98:99], v[112:113] op_sel_hi:[1,0]
	v_pk_mul_f32 v[98:99], v[96:97], v[112:113] op_sel_hi:[1,0]
	v_pk_mul_f32 v[100:101], v[100:101], v[112:113] op_sel_hi:[1,0]
	v_pk_mul_f32 v[110:111], v[110:111], v[112:113] op_sel_hi:[1,0]
	v_pk_mul_f32 v[102:103], v[102:103], v[112:113] op_sel_hi:[1,0]
	v_pk_mul_f32 v[104:105], v[104:105], v[112:113] op_sel_hi:[1,0]
	v_pk_mul_f32 v[106:107], v[106:107], v[112:113] op_sel_hi:[1,0]
	v_pk_mul_f32 v[154:155], v[108:109], s[100:101]
	v_pk_mul_f32 v[156:157], v[110:111], s[100:101]
	v_exp_f32_e32 v154, v154
	v_exp_f32_e32 v155, v155
	v_exp_f32_e32 v156, v156
	v_exp_f32_e32 v157, v157
	v_pk_add_f32 v[154:155], v[154:155], 1.0 op_sel_hi:[1,0]
	v_pk_add_f32 v[156:157], v[156:157], 1.0 op_sel_hi:[1,0]
	v_rcp_f32_e32 v154, v154
	v_rcp_f32_e32 v155, v155
	v_rcp_f32_e32 v156, v156
	v_rcp_f32_e32 v157, v157
	v_pk_mul_f32 v[154:155], v[108:109], v[154:155]
	v_pk_mul_f32 v[156:157], v[110:111], v[156:157]
	v_pk_mul_f32 v[154:155], v[100:101], v[154:155]
	v_pk_mul_f32 v[156:157], v[102:103], v[156:157]
	v_pk_mul_f32 v[158:159], v[104:105], s[100:101]
	v_pk_mul_f32 v[160:161], v[106:107], s[100:101]
	v_exp_f32_e32 v158, v158
	v_exp_f32_e32 v159, v159
	v_exp_f32_e32 v160, v160
	v_exp_f32_e32 v161, v161
	v_pk_add_f32 v[158:159], v[158:159], 1.0 op_sel_hi:[1,0]
	v_pk_add_f32 v[160:161], v[160:161], 1.0 op_sel_hi:[1,0]
	v_rcp_f32_e32 v158, v158
	v_rcp_f32_e32 v159, v159
	v_rcp_f32_e32 v160, v160
	v_rcp_f32_e32 v161, v161
	v_pk_mul_f32 v[158:159], v[104:105], v[158:159]
	v_pk_mul_f32 v[160:161], v[106:107], v[160:161]
	v_pk_mul_f32 v[158:159], v[98:99], v[158:159]
	v_pk_mul_f32 v[160:161], v[114:115], v[160:161]
	v_cvt_pk_bf16_f32 v96, v154, v155
	v_cvt_pk_bf16_f32 v97, v156, v157
	v_cvt_pk_bf16_f32 v98, v158, v159
	v_cvt_pk_bf16_f32 v99, v160, v161
	s_nop 0
	s_nop 0
	s_nop 0
	s_nop 0
	global_store_dwordx4 v[164:165], v[96:99], off offset:-2048
	s_nop 1
; __device__ __forceinline__ unsigned cvt_pk_bf16(float lo, float hi) { unsigned r; asm volatile("v_cvt_pk_bf16_f32 %0, %1, %2" : "=v"(r) : "v"(lo), "v"(hi)); return r; }
; __device__ __forceinline__ float silu_mul(float g, float u) { return g * __builtin_amdgcn_rcpf(1.0f + __builtin_amdgcn_exp2f(-1.4426950408889634f * g)) * u; }
;     __device__ __forceinline__ void operator()(const f32x4 (&acc)[2][2][4][2], const Unit& u, int wr, int wc, int fr, int fq) const {
;     ...
;             for (int m = 0; m < 4; ++m) {
;                 const int row = row0 + ai * HALF + m * 16;
;                 const float r = __builtin_amdgcn_rsqf(rs[ai][m] * (1.0f / DM) + EPSN);
;                 const f32x4 g0 = acc[ai][0][m][0] * r, g1 = acc[ai][0][m][1] * r, u0 = acc[ai][1][m][0] * r, u1 = acc[ai][1][m][1] * r;
;                 u32x4 w;
;                 w.x = cvt_pk_bf16(silu_mul(g0[0], u0[0]), silu_mul(g0[1], u0[1])); w.y = cvt_pk_bf16(silu_mul(g0[2], u0[2]), silu_mul(g0[3], u0[3]));
;                 w.z = cvt_pk_bf16(silu_mul(g1[0], u1[0]), silu_mul(g1[1], u1[1])); w.w = cvt_pk_bf16(silu_mul(g1[2], u1[2]), silu_mul(g1[3], u1[3]));
;                 *(u32x4*)(act + (((size_t)u.pm * (DFF / 64) + (u.pn * 2 + (wc >> 1))) * 256 + (row - u.pm * BM)) * 64 + (wc & 1) * 32 + 8 * fq) = w;
	v_fmamk_f32 v96, v153, 0x3a000000, v145
	v_rsq_f32_e32 v96, v96
	s_nop 0
	v_pk_mul_f32 v[92:93], v[92:93], v[96:97] op_sel_hi:[1,0]
	v_pk_mul_f32 v[98:99], v[82:83], v[96:97] op_sel_hi:[1,0]
	v_pk_mul_f32 v[82:83], v[80:81], v[96:97] op_sel_hi:[1,0]
	v_pk_mul_f32 v[84:85], v[84:85], v[96:97] op_sel_hi:[1,0]
	v_pk_mul_f32 v[94:95], v[94:95], v[96:97] op_sel_hi:[1,0]
	v_pk_mul_f32 v[86:87], v[86:87], v[96:97] op_sel_hi:[1,0]
	v_pk_mul_f32 v[88:89], v[88:89], v[96:97] op_sel_hi:[1,0]
	v_pk_mul_f32 v[90:91], v[90:91], v[96:97] op_sel_hi:[1,0]
	v_pk_mul_f32 v[154:155], v[92:93], s[100:101]
	v_pk_mul_f32 v[156:157], v[94:95], s[100:101]
	v_exp_f32_e32 v154, v154
	v_exp_f32_e32 v155, v155
	v_exp_f32_e32 v156, v156
	v_exp_f32_e32 v157, v157
	v_pk_add_f32 v[154:155], v[154:155], 1.0 op_sel_hi:[1,0]
	v_pk_add_f32 v[156:157], v[156:157], 1.0 op_sel_hi:[1,0]
	v_rcp_f32_e32 v154, v154
	v_rcp_f32_e32 v155, v155
	v_rcp_f32_e32 v156, v156
	v_rcp_f32_e32 v157, v157
	v_pk_mul_f32 v[154:155], v[92:93], v[154:155]
	v_pk_mul_f32 v[156:157], v[94:95], v[156:157]
	v_pk_mul_f32 v[154:155], v[84:85], v[154:155]
	v_pk_mul_f32 v[156:157], v[86:87], v[156:157]
	v_pk_mul_f32 v[158:159], v[88:89], s[100:101]
	v_pk_mul_f32 v[160:161], v[90:91], s[100:101]
	v_exp_f32_e32 v158, v158
	v_exp_f32_e32 v159, v159
	v_exp_f32_e32 v160, v160
	v_exp_f32_e32 v161, v161
	v_pk_add_f32 v[158:159], v[158:159], 1.0 op_sel_hi:[1,0]
	v_pk_add_f32 v[160:161], v[160:161], 1.0 op_sel_hi:[1,0]
	v_rcp_f32_e32 v158, v158
	v_rcp_f32_e32 v159, v159
	v_rcp_f32_e32 v160, v160
	v_rcp_f32_e32 v161, v161
	v_pk_mul_f32 v[158:159], v[88:89], v[158:159]
	v_pk_mul_f32 v[160:161], v[90:91], v[160:161]
	v_pk_mul_f32 v[158:159], v[82:83], v[158:159]
	v_pk_mul_f32 v[160:161], v[98:99], v[160:161]
	v_cvt_pk_bf16_f32 v80, v154, v155
	v_cvt_pk_bf16_f32 v81, v156, v157
	v_cvt_pk_bf16_f32 v82, v158, v159
	v_cvt_pk_bf16_f32 v83, v160, v161
	s_nop 0
	s_nop 0
	s_nop 0
	s_nop 0
	global_store_dwordx4 v[164:165], v[80:83], off
	s_nop 1
	v_fmamk_f32 v80, v147, 0x3a000000, v145
	v_rsq_f32_e32 v80, v80
	s_nop 0
	v_pk_mul_f32 v[76:77], v[76:77], v[80:81] op_sel_hi:[1,0]
	v_pk_mul_f32 v[82:83], v[66:67], v[80:81] op_sel_hi:[1,0]
	v_pk_mul_f32 v[66:67], v[64:65], v[80:81] op_sel_hi:[1,0]
	v_pk_mul_f32 v[68:69], v[68:69], v[80:81] op_sel_hi:[1,0]
	v_pk_mul_f32 v[78:79], v[78:79], v[80:81] op_sel_hi:[1,0]
	v_pk_mul_f32 v[70:71], v[70:71], v[80:81] op_sel_hi:[1,0]
	v_pk_mul_f32 v[72:73], v[72:73], v[80:81] op_sel_hi:[1,0]
	v_pk_mul_f32 v[74:75], v[74:75], v[80:81] op_sel_hi:[1,0]
	v_pk_mul_f32 v[154:155], v[76:77], s[100:101]
	v_pk_mul_f32 v[156:157], v[78:79], s[100:101]
	v_exp_f32_e32 v154, v154
	v_exp_f32_e32 v155, v155
	v_exp_f32_e32 v156, v156
	v_exp_f32_e32 v157, v157
	v_pk_add_f32 v[154:155], v[154:155], 1.0 op_sel_hi:[1,0]
	v_pk_add_f32 v[156:157], v[156:157], 1.0 op_sel_hi:[1,0]
	v_rcp_f32_e32 v154, v154
	v_rcp_f32_e32 v155, v155
	v_rcp_f32_e32 v156, v156
	v_rcp_f32_e32 v157, v157
	v_pk_mul_f32 v[154:155], v[76:77], v[154:155]
	v_pk_mul_f32 v[156:157], v[78:79], v[156:157]
	v_pk_mul_f32 v[154:155], v[68:69], v[154:155]
	v_pk_mul_f32 v[156:157], v[70:71], v[156:157]
	v_pk_mul_f32 v[158:159], v[72:73], s[100:101]
	v_pk_mul_f32 v[160:161], v[74:75], s[100:101]
	v_exp_f32_e32 v158, v158
	v_exp_f32_e32 v159, v159
	v_exp_f32_e32 v160, v160
	v_exp_f32_e32 v161, v161
	v_pk_add_f32 v[158:159], v[158:159], 1.0 op_sel_hi:[1,0]
	v_pk_add_f32 v[160:161], v[160:161], 1.0 op_sel_hi:[1,0]
	v_rcp_f32_e32 v158, v158
	v_rcp_f32_e32 v159, v159
	v_rcp_f32_e32 v160, v160
	v_rcp_f32_e32 v161, v161
	v_pk_mul_f32 v[158:159], v[72:73], v[158:159]
	v_pk_mul_f32 v[160:161], v[74:75], v[160:161]
	v_pk_mul_f32 v[158:159], v[66:67], v[158:159]
	v_pk_mul_f32 v[160:161], v[82:83], v[160:161]
	v_cvt_pk_bf16_f32 v64, v154, v155
	v_cvt_pk_bf16_f32 v65, v156, v157
	v_cvt_pk_bf16_f32 v66, v158, v159
	v_cvt_pk_bf16_f32 v67, v160, v161
	s_nop 0
	s_nop 0
	s_nop 0
	s_nop 0
	global_store_dwordx4 v[164:165], v[64:67], off offset:2048
	s_nop 1
	v_fmamk_f32 v64, v146, 0x3a000000, v145
	v_rsq_f32_e32 v64, v64
	s_nop 0
	v_pk_mul_f32 v[60:61], v[60:61], v[64:65] op_sel_hi:[1,0]
	v_pk_mul_f32 v[66:67], v[50:51], v[64:65] op_sel_hi:[1,0]
	v_pk_mul_f32 v[50:51], v[48:49], v[64:65] op_sel_hi:[1,0]
	v_pk_mul_f32 v[52:53], v[52:53], v[64:65] op_sel_hi:[1,0]
	v_pk_mul_f32 v[62:63], v[62:63], v[64:65] op_sel_hi:[1,0]
	v_pk_mul_f32 v[54:55], v[54:55], v[64:65] op_sel_hi:[1,0]
	v_pk_mul_f32 v[56:57], v[56:57], v[64:65] op_sel_hi:[1,0]
	v_pk_mul_f32 v[58:59], v[58:59], v[64:65] op_sel_hi:[1,0]
	v_pk_mul_f32 v[154:155], v[60:61], s[100:101]
	v_pk_mul_f32 v[156:157], v[62:63], s[100:101]
	v_exp_f32_e32 v154, v154
	v_exp_f32_e32 v155, v155
	v_exp_f32_e32 v156, v156
	v_exp_f32_e32 v157, v157
	v_pk_add_f32 v[154:155], v[154:155], 1.0 op_sel_hi:[1,0]
	v_pk_add_f32 v[156:157], v[156:157], 1.0 op_sel_hi:[1,0]
	v_rcp_f32_e32 v154, v154
	v_rcp_f32_e32 v155, v155
	v_rcp_f32_e32 v156, v156
	v_rcp_f32_e32 v157, v157
	v_pk_mul_f32 v[154:155], v[60:61], v[154:155]
	v_pk_mul_f32 v[156:157], v[62:63], v[156:157]
	v_pk_mul_f32 v[154:155], v[52:53], v[154:155]
	v_pk_mul_f32 v[156:157], v[54:55], v[156:157]
	v_pk_mul_f32 v[158:159], v[56:57], s[100:101]
	v_pk_mul_f32 v[160:161], v[58:59], s[100:101]
	v_exp_f32_e32 v158, v158
	v_exp_f32_e32 v159, v159
	v_exp_f32_e32 v160, v160
	v_exp_f32_e32 v161, v161
	v_pk_add_f32 v[158:159], v[158:159], 1.0 op_sel_hi:[1,0]
	v_pk_add_f32 v[160:161], v[160:161], 1.0 op_sel_hi:[1,0]
	v_rcp_f32_e32 v158, v158
	v_rcp_f32_e32 v159, v159
	v_rcp_f32_e32 v160, v160
	v_rcp_f32_e32 v161, v161
	v_pk_mul_f32 v[158:159], v[56:57], v[158:159]
	v_pk_mul_f32 v[160:161], v[58:59], v[160:161]
; __device__ __forceinline__ unsigned cvt_pk_bf16(float lo, float hi) { unsigned r; asm volatile("v_cvt_pk_bf16_f32 %0, %1, %2" : "=v"(r) : "v"(lo), "v"(hi)); return r; }
; __device__ __forceinline__ float silu_mul(float g, float u) { return g * __builtin_amdgcn_rcpf(1.0f + __builtin_amdgcn_exp2f(-1.4426950408889634f * g)) * u; }
;     __device__ __forceinline__ void operator()(const f32x4 (&acc)[2][2][4][2], const Unit& u, int wr, int wc, int fr, int fq) const {
;     ...
;             for (int m = 0; m < 4; ++m) {
;                 const int row = row0 + ai * HALF + m * 16;
;                 const float r = __builtin_amdgcn_rsqf(rs[ai][m] * (1.0f / DM) + EPSN);
;                 const f32x4 g0 = acc[ai][0][m][0] * r, g1 = acc[ai][0][m][1] * r, u0 = acc[ai][1][m][0] * r, u1 = acc[ai][1][m][1] * r;
;                 u32x4 w;
;                 w.x = cvt_pk_bf16(silu_mul(g0[0], u0[0]), silu_mul(g0[1], u0[1])); w.y = cvt_pk_bf16(silu_mul(g0[2], u0[2]), silu_mul(g0[3], u0[3]));
;                 w.z = cvt_pk_bf16(silu_mul(g1[0], u1[0]), silu_mul(g1[1], u1[1])); w.w = cvt_pk_bf16(silu_mul(g1[2], u1[2]), silu_mul(g1[3], u1[3]));
;                 *(u32x4*)(act + (((size_t)u.pm * (DFF / 64) + (u.pn * 2 + (wc >> 1))) * 256 + (row - u.pm * BM)) * 64 + (wc & 1) * 32 + 8 * fq) = w;
	v_pk_mul_f32 v[158:159], v[50:51], v[158:159]
	v_pk_mul_f32 v[160:161], v[66:67], v[160:161]
	v_cvt_pk_bf16_f32 v48, v154, v155
	v_cvt_pk_bf16_f32 v49, v156, v157
	v_cvt_pk_bf16_f32 v50, v158, v159
	v_cvt_pk_bf16_f32 v51, v160, v161
	s_nop 0
	s_nop 0
	s_nop 0
	s_nop 0
	global_store_dwordx4 v[166:167], v[48:51], off offset:-4096
	s_nop 1
	v_fmamk_f32 v48, v141, 0x3a000000, v145
	v_rsq_f32_e32 v48, v48
	s_nop 0
	v_pk_mul_f32 v[44:45], v[44:45], v[48:49] op_sel_hi:[1,0]
	v_pk_mul_f32 v[50:51], v[34:35], v[48:49] op_sel_hi:[1,0]
	v_pk_mul_f32 v[34:35], v[32:33], v[48:49] op_sel_hi:[1,0]
	v_pk_mul_f32 v[36:37], v[36:37], v[48:49] op_sel_hi:[1,0]
	v_pk_mul_f32 v[46:47], v[46:47], v[48:49] op_sel_hi:[1,0]
	v_pk_mul_f32 v[38:39], v[38:39], v[48:49] op_sel_hi:[1,0]
	v_pk_mul_f32 v[40:41], v[40:41], v[48:49] op_sel_hi:[1,0]
	v_pk_mul_f32 v[42:43], v[42:43], v[48:49] op_sel_hi:[1,0]
	v_pk_mul_f32 v[154:155], v[44:45], s[100:101]
	v_pk_mul_f32 v[156:157], v[46:47], s[100:101]
	v_exp_f32_e32 v154, v154
	v_exp_f32_e32 v155, v155
	v_exp_f32_e32 v156, v156
	v_exp_f32_e32 v157, v157
	v_pk_add_f32 v[154:155], v[154:155], 1.0 op_sel_hi:[1,0]
	v_pk_add_f32 v[156:157], v[156:157], 1.0 op_sel_hi:[1,0]
	v_rcp_f32_e32 v154, v154
	v_rcp_f32_e32 v155, v155
	v_rcp_f32_e32 v156, v156
	v_rcp_f32_e32 v157, v157
	v_pk_mul_f32 v[154:155], v[44:45], v[154:155]
	v_pk_mul_f32 v[156:157], v[46:47], v[156:157]
	v_pk_mul_f32 v[154:155], v[36:37], v[154:155]
	v_pk_mul_f32 v[156:157], v[38:39], v[156:157]
	v_pk_mul_f32 v[158:159], v[40:41], s[100:101]
	v_pk_mul_f32 v[160:161], v[42:43], s[100:101]
	v_exp_f32_e32 v158, v158
	v_exp_f32_e32 v159, v159
	v_exp_f32_e32 v160, v160
	v_exp_f32_e32 v161, v161
	v_pk_add_f32 v[158:159], v[158:159], 1.0 op_sel_hi:[1,0]
	v_pk_add_f32 v[160:161], v[160:161], 1.0 op_sel_hi:[1,0]
	v_rcp_f32_e32 v158, v158
	v_rcp_f32_e32 v159, v159
	v_rcp_f32_e32 v160, v160
	v_rcp_f32_e32 v161, v161
	v_pk_mul_f32 v[158:159], v[40:41], v[158:159]
	v_pk_mul_f32 v[160:161], v[42:43], v[160:161]
	v_pk_mul_f32 v[158:159], v[34:35], v[158:159]
	v_pk_mul_f32 v[160:161], v[50:51], v[160:161]
	v_cvt_pk_bf16_f32 v32, v154, v155
	v_cvt_pk_bf16_f32 v33, v156, v157
	v_cvt_pk_bf16_f32 v34, v158, v159
	v_cvt_pk_bf16_f32 v35, v160, v161
	s_nop 0
	s_nop 0
	s_nop 0
	s_nop 0
	global_store_dwordx4 v[166:167], v[32:35], off offset:-2048
	s_nop 1
	v_fmamk_f32 v32, v139, 0x3a000000, v145
	v_rsq_f32_e32 v32, v32
	s_nop 0
	v_pk_mul_f32 v[28:29], v[28:29], v[32:33] op_sel_hi:[1,0]
	v_pk_mul_f32 v[34:35], v[18:19], v[32:33] op_sel_hi:[1,0]
	v_pk_mul_f32 v[18:19], v[16:17], v[32:33] op_sel_hi:[1,0]
	v_pk_mul_f32 v[20:21], v[20:21], v[32:33] op_sel_hi:[1,0]
	v_pk_mul_f32 v[30:31], v[30:31], v[32:33] op_sel_hi:[1,0]
	v_pk_mul_f32 v[22:23], v[22:23], v[32:33] op_sel_hi:[1,0]
	v_pk_mul_f32 v[24:25], v[24:25], v[32:33] op_sel_hi:[1,0]
	v_pk_mul_f32 v[26:27], v[26:27], v[32:33] op_sel_hi:[1,0]
	v_pk_mul_f32 v[154:155], v[28:29], s[100:101]
	v_pk_mul_f32 v[156:157], v[30:31], s[100:101]
	v_exp_f32_e32 v154, v154
	v_exp_f32_e32 v155, v155
	v_exp_f32_e32 v156, v156
	v_exp_f32_e32 v157, v157
	v_pk_add_f32 v[154:155], v[154:155], 1.0 op_sel_hi:[1,0]
	v_pk_add_f32 v[156:157], v[156:157], 1.0 op_sel_hi:[1,0]
	v_rcp_f32_e32 v154, v154
	v_rcp_f32_e32 v155, v155
	v_rcp_f32_e32 v156, v156
	v_rcp_f32_e32 v157, v157
	v_pk_mul_f32 v[154:155], v[28:29], v[154:155]
	v_pk_mul_f32 v[156:157], v[30:31], v[156:157]
	v_pk_mul_f32 v[154:155], v[20:21], v[154:155]
	v_pk_mul_f32 v[156:157], v[22:23], v[156:157]
	v_pk_mul_f32 v[158:159], v[24:25], s[100:101]
	v_pk_mul_f32 v[160:161], v[26:27], s[100:101]
	v_exp_f32_e32 v158, v158
	v_exp_f32_e32 v159, v159
	v_exp_f32_e32 v160, v160
	v_exp_f32_e32 v161, v161
	v_pk_add_f32 v[158:159], v[158:159], 1.0 op_sel_hi:[1,0]
	v_pk_add_f32 v[160:161], v[160:161], 1.0 op_sel_hi:[1,0]
	v_rcp_f32_e32 v158, v158
	v_rcp_f32_e32 v159, v159
	v_rcp_f32_e32 v160, v160
	v_rcp_f32_e32 v161, v161
	v_pk_mul_f32 v[158:159], v[24:25], v[158:159]
	v_pk_mul_f32 v[160:161], v[26:27], v[160:161]
	v_pk_mul_f32 v[158:159], v[18:19], v[158:159]
	v_pk_mul_f32 v[160:161], v[34:35], v[160:161]
	v_cvt_pk_bf16_f32 v16, v154, v155
	v_cvt_pk_bf16_f32 v17, v156, v157
	v_cvt_pk_bf16_f32 v18, v158, v159
	v_cvt_pk_bf16_f32 v19, v160, v161
	s_nop 0
	s_nop 0
	s_nop 0
	s_nop 0
	global_store_dwordx4 v[166:167], v[16:19], off
	s_nop 1
	v_fmamk_f32 v16, v137, 0x3a000000, v145
	v_rsq_f32_e32 v16, v16
	s_nop 0
	v_pk_mul_f32 v[12:13], v[12:13], v[16:17] op_sel_hi:[1,0]
	v_pk_mul_f32 v[18:19], v[2:3], v[16:17] op_sel_hi:[1,0]
	v_pk_mul_f32 v[2:3], v[0:1], v[16:17] op_sel_hi:[1,0]
	v_pk_mul_f32 v[4:5], v[4:5], v[16:17] op_sel_hi:[1,0]
	v_pk_mul_f32 v[14:15], v[14:15], v[16:17] op_sel_hi:[1,0]
	v_pk_mul_f32 v[6:7], v[6:7], v[16:17] op_sel_hi:[1,0]
	v_pk_mul_f32 v[8:9], v[8:9], v[16:17] op_sel_hi:[1,0]
	v_pk_mul_f32 v[10:11], v[10:11], v[16:17] op_sel_hi:[1,0]
	v_pk_mul_f32 v[154:155], v[12:13], s[100:101]
	v_pk_mul_f32 v[156:157], v[14:15], s[100:101]
	v_exp_f32_e32 v154, v154
	v_exp_f32_e32 v155, v155
	v_exp_f32_e32 v156, v156
	v_exp_f32_e32 v157, v157
	v_pk_add_f32 v[154:155], v[154:155], 1.0 op_sel_hi:[1,0]
	v_pk_add_f32 v[156:157], v[156:157], 1.0 op_sel_hi:[1,0]
	v_rcp_f32_e32 v154, v154
	v_rcp_f32_e32 v155, v155
	v_rcp_f32_e32 v156, v156
	v_rcp_f32_e32 v157, v157
	v_pk_mul_f32 v[154:155], v[12:13], v[154:155]
	v_pk_mul_f32 v[156:157], v[14:15], v[156:157]
	v_pk_mul_f32 v[154:155], v[4:5], v[154:155]
	v_pk_mul_f32 v[156:157], v[6:7], v[156:157]
	v_pk_mul_f32 v[158:159], v[8:9], s[100:101]
	v_pk_mul_f32 v[160:161], v[10:11], s[100:101]
	v_exp_f32_e32 v158, v158
	v_exp_f32_e32 v159, v159
	v_exp_f32_e32 v160, v160
	v_exp_f32_e32 v161, v161
	v_pk_add_f32 v[158:159], v[158:159], 1.0 op_sel_hi:[1,0]
	v_pk_add_f32 v[160:161], v[160:161], 1.0 op_sel_hi:[1,0]
	v_rcp_f32_e32 v158, v158
	v_rcp_f32_e32 v159, v159
	v_rcp_f32_e32 v160, v160
	v_rcp_f32_e32 v161, v161
	v_pk_mul_f32 v[158:159], v[8:9], v[158:159]
	v_pk_mul_f32 v[160:161], v[10:11], v[160:161]
	v_pk_mul_f32 v[158:159], v[2:3], v[158:159]
	v_pk_mul_f32 v[160:161], v[18:19], v[160:161]
	v_cvt_pk_bf16_f32 v0, v154, v155
	v_cvt_pk_bf16_f32 v1, v156, v157
	v_cvt_pk_bf16_f32 v2, v158, v159
	v_cvt_pk_bf16_f32 v3, v160, v161
	s_nop 0
	s_nop 0
	s_nop 0
	s_nop 0
	global_store_dwordx4 v[166:167], v[0:3], off offset:2048
	s_andn2_b64 vcc, exec, s[30:31]
	s_mov_b64 s[30:31], -1
	s_cbranch_vccnz .LBB0_269
	s_andn2_b64 vcc, exec, s[0:1]
	s_cbranch_vccnz .LBB0_268
	s_barrier
	s_branch .LBB0_268

; __device__ __forceinline__ unsigned cvt_pk_bf16(float lo, float hi) { unsigned r; asm volatile("v_cvt_pk_bf16_f32 %0, %1, %2" : "=v"(r) : "v"(lo), "v"(hi)); return r; }
; __device__ __forceinline__ float silu_mul(float g, float u) { return g * __builtin_amdgcn_rcpf(1.0f + __builtin_amdgcn_exp2f(-1.4426950408889634f * g)) * u; }
;     __device__ __forceinline__ void operator()(const f32x4 (&acc)[2][2][4][2], const Unit& u, int wr, int wc, int fr, int fq) const {
;         const int row0 = u.pm * BM + wr * 64 + fr, j0 = u.pn * HALF + wc * 32 + 8 * fq;
;         float rs[2][4];
; #pragma unroll
;         for (int ai = 0; ai < 2; ++ai)
; #pragma unroll
;             for (int m = 0; m < 4; ++m) rs[ai][m] = ss[row0 + ai * HALF + m * 16];
;         __builtin_amdgcn_sched_barrier(0);
; #pragma unroll
;         for (int ai = 0; ai < 2; ++ai)
; #pragma unroll
;             for (int m = 0; m < 4; ++m) {
;                 const int row = row0 + ai * HALF + m * 16;
;                 const float r = __builtin_amdgcn_rsqf(rs[ai][m] * (1.0f / DM) + EPSN);
;                 const f32x4 g0 = acc[ai][0][m][0] * r, g1 = acc[ai][0][m][1] * r, u0 = acc[ai][1][m][0] * r, u1 = acc[ai][1][m][1] * r;
;                 u32x4 w;
;                 w.x = cvt_pk_bf16(silu_mul(g0[0], u0[0]), silu_mul(g0[1], u0[1])); w.y = cvt_pk_bf16(silu_mul(g0[2], u0[2]), silu_mul(g0[3], u0[3]));
;                 w.z = cvt_pk_bf16(silu_mul(g1[0], u1[0]), silu_mul(g1[1], u1[1])); w.w = cvt_pk_bf16(silu_mul(g1[2], u1[2]), silu_mul(g1[3], u1[3]));
;                 *(u32x4*)(act + (((size_t)u.pm * (DFF / 64) + (u.pn * 2 + (wc >> 1))) * 256 + (row - u.pm * BM)) * 64 + (wc & 1) * 32 + 8 * fq) = w;
.LBB0_1342:
	s_lshl_b32 s21, s30, 8
	v_add_u32_e32 v136, s21, v128
	v_ashrrev_i32_e32 v137, 31, v136
	v_lshl_add_u64 v[146:147], v[136:137], 2, s[76:77]
	v_or_b32_e32 v148, 16, v136
	v_or_b32_e32 v138, 32, v136
	v_or_b32_e32 v136, 48, v136
	v_ashrrev_i32_e32 v149, 31, v148
	v_ashrrev_i32_e32 v137, 31, v136
	v_lshl_add_u64 v[144:145], v[148:149], 2, s[76:77]
	v_ashrrev_i32_e32 v139, 31, v138
	v_lshl_add_u64 v[152:153], v[136:137], 2, s[76:77]
	v_lshl_add_u64 v[150:151], v[138:139], 2, s[76:77]
	global_load_dword v149, v[146:147], off
	s_nop 0
	global_load_dword v145, v[144:145], off
	s_nop 0
	global_load_dword v154, v[150:151], off
	s_nop 0
	global_load_dword v152, v[152:153], off
	s_nop 0
	global_load_dword v153, v[146:147], off offset:512
	global_load_dword v144, v[146:147], off offset:576
	global_load_dword v139, v[146:147], off offset:640
	global_load_dword v137, v[146:147], off offset:704
	s_waitcnt vmcnt(0)
	s_mov_b32 s98, 0x1000
	s_mov_b32 s99, 0
	s_mov_b32 s100, 0xbfb8aa3b
	s_mov_b32 s101, 0xbfb8aa3b
	v_fmamk_f32 v146, v149, 0x3a000000, v143
	v_rsq_f32_e32 v146, v146
	s_lshl_b32 s31, s31, 1
	s_or_b32 s31, s31, s45
	s_mul_hi_i32 s23, s30, 0x56
	v_pk_mul_f32 v[124:125], v[124:125], v[146:147] op_sel_hi:[1,0]
	v_pk_mul_f32 v[126:127], v[126:127], v[146:147] op_sel_hi:[1,0]
	v_pk_mul_f32 v[122:123], v[122:123], v[146:147] op_sel_hi:[1,0]
	v_pk_mul_f32 v[120:121], v[120:121], v[146:147] op_sel_hi:[1,0]
	v_pk_mul_f32 v[118:119], v[118:119], v[146:147] op_sel_hi:[1,0]
	v_pk_mul_f32 v[116:117], v[116:117], v[146:147] op_sel_hi:[1,0]
	s_mulk_i32 s30, 0x56
	v_pk_mul_f32 v[150:151], v[114:115], v[146:147] op_sel_hi:[1,0]
	s_ashr_i32 s34, s31, 31
	v_pk_mul_f32 v[114:115], v[112:113], v[146:147] op_sel_hi:[1,0]
	v_pk_mul_f32 v[156:157], v[124:125], s[100:101]
	v_pk_mul_f32 v[158:159], v[126:127], s[100:101]
	v_exp_f32_e32 v156, v156
	v_exp_f32_e32 v157, v157
	v_exp_f32_e32 v158, v158
	v_exp_f32_e32 v159, v159
	v_pk_add_f32 v[156:157], v[156:157], 1.0 op_sel_hi:[1,0]
	v_pk_add_f32 v[158:159], v[158:159], 1.0 op_sel_hi:[1,0]
	v_rcp_f32_e32 v156, v156
	v_rcp_f32_e32 v157, v157
	v_rcp_f32_e32 v158, v158
	v_rcp_f32_e32 v159, v159
	v_pk_mul_f32 v[156:157], v[124:125], v[156:157]
	v_pk_mul_f32 v[158:159], v[126:127], v[158:159]
	v_pk_mul_f32 v[156:157], v[116:117], v[156:157]
	v_pk_mul_f32 v[158:159], v[118:119], v[158:159]
	v_pk_mul_f32 v[160:161], v[120:121], s[100:101]
	v_pk_mul_f32 v[162:163], v[122:123], s[100:101]
	v_exp_f32_e32 v160, v160
	v_exp_f32_e32 v161, v161
	v_exp_f32_e32 v162, v162
	v_exp_f32_e32 v163, v163
	v_pk_add_f32 v[160:161], v[160:161], 1.0 op_sel_hi:[1,0]
	v_pk_add_f32 v[162:163], v[162:163], 1.0 op_sel_hi:[1,0]
	v_rcp_f32_e32 v160, v160
	v_rcp_f32_e32 v161, v161
	v_rcp_f32_e32 v162, v162
	v_rcp_f32_e32 v163, v163
	v_pk_mul_f32 v[160:161], v[120:121], v[160:161]
	v_pk_mul_f32 v[162:163], v[122:123], v[162:163]
	v_pk_mul_f32 v[160:161], v[114:115], v[160:161]
	v_pk_mul_f32 v[162:163], v[150:151], v[162:163]
	v_cvt_pk_bf16_f32 v112, v156, v157
	v_cvt_pk_bf16_f32 v113, v158, v159
	v_cvt_pk_bf16_f32 v114, v160, v161
	v_cvt_pk_bf16_f32 v115, v162, v163
	s_add_u32 s30, s30, s31
	s_addc_u32 s31, s23, s34
	s_lshl_b64 s[30:31], s[30:31], 15
	s_add_u32 s30, s4, s30
	s_addc_u32 s31, s5, s31
	v_lshl_add_u64 v[116:117], s[30:31], 0, v[130:131]
	v_lshl_add_u64 v[116:117], v[116:117], 0, s[16:17]
	v_lshl_add_u64 v[116:117], v[116:117], 0, v[200:201]
	v_lshl_add_u64 v[164:165], v[116:117], 0, s[98:99]
	v_lshl_add_u64 v[166:167], s[98:99], 2, v[164:165]
	global_store_dwordx4 v[116:117], v[112:115], off
	s_nop 1
	v_fmamk_f32 v112, v145, 0x3a000000, v143
	v_rsq_f32_e32 v112, v112
	s_nop 0
	v_pk_mul_f32 v[108:109], v[108:109], v[112:113] op_sel_hi:[1,0]
	v_pk_mul_f32 v[110:111], v[110:111], v[112:113] op_sel_hi:[1,0]
	v_pk_mul_f32 v[106:107], v[106:107], v[112:113] op_sel_hi:[1,0]
	v_pk_mul_f32 v[104:105], v[104:105], v[112:113] op_sel_hi:[1,0]
	v_pk_mul_f32 v[102:103], v[102:103], v[112:113] op_sel_hi:[1,0]
	v_pk_mul_f32 v[100:101], v[100:101], v[112:113] op_sel_hi:[1,0]
	v_pk_mul_f32 v[114:115], v[98:99], v[112:113] op_sel_hi:[1,0]
	v_pk_mul_f32 v[98:99], v[96:97], v[112:113] op_sel_hi:[1,0]
	v_pk_mul_f32 v[156:157], v[108:109], s[100:101]
	v_pk_mul_f32 v[158:159], v[110:111], s[100:101]
	v_exp_f32_e32 v156, v156
	v_exp_f32_e32 v157, v157
	v_exp_f32_e32 v158, v158
	v_exp_f32_e32 v159, v159
	v_pk_add_f32 v[156:157], v[156:157], 1.0 op_sel_hi:[1,0]
	v_pk_add_f32 v[158:159], v[158:159], 1.0 op_sel_hi:[1,0]
	v_rcp_f32_e32 v156, v156
	v_rcp_f32_e32 v157, v157
	v_rcp_f32_e32 v158, v158
	v_rcp_f32_e32 v159, v159
	v_pk_mul_f32 v[156:157], v[108:109], v[156:157]
	v_pk_mul_f32 v[158:159], v[110:111], v[158:159]
	v_pk_mul_f32 v[156:157], v[100:101], v[156:157]
	v_pk_mul_f32 v[158:159], v[102:103], v[158:159]
	v_pk_mul_f32 v[160:161], v[104:105], s[100:101]
	v_pk_mul_f32 v[162:163], v[106:107], s[100:101]
	v_exp_f32_e32 v160, v160
	v_exp_f32_e32 v161, v161
	v_exp_f32_e32 v162, v162
	v_exp_f32_e32 v163, v163
	v_pk_add_f32 v[160:161], v[160:161], 1.0 op_sel_hi:[1,0]
	v_pk_add_f32 v[162:163], v[162:163], 1.0 op_sel_hi:[1,0]
	v_rcp_f32_e32 v160, v160
	v_rcp_f32_e32 v161, v161
	v_rcp_f32_e32 v162, v162
	v_rcp_f32_e32 v163, v163
	v_pk_mul_f32 v[160:161], v[104:105], v[160:161]
	v_pk_mul_f32 v[162:163], v[106:107], v[162:163]
	v_pk_mul_f32 v[160:161], v[98:99], v[160:161]
	v_pk_mul_f32 v[162:163], v[114:115], v[162:163]
	v_cvt_pk_bf16_f32 v96, v156, v157
	v_cvt_pk_bf16_f32 v97, v158, v159
	v_cvt_pk_bf16_f32 v98, v160, v161
	v_cvt_pk_bf16_f32 v99, v162, v163
	global_store_dwordx4 v[164:165], v[96:99], off offset:-2048
	s_nop 1
	v_fmamk_f32 v96, v154, 0x3a000000, v143
; __device__ __forceinline__ unsigned cvt_pk_bf16(float lo, float hi) { unsigned r; asm volatile("v_cvt_pk_bf16_f32 %0, %1, %2" : "=v"(r) : "v"(lo), "v"(hi)); return r; }
; __device__ __forceinline__ float silu_mul(float g, float u) { return g * __builtin_amdgcn_rcpf(1.0f + __builtin_amdgcn_exp2f(-1.4426950408889634f * g)) * u; }
;     __device__ __forceinline__ void operator()(const f32x4 (&acc)[2][2][4][2], const Unit& u, int wr, int wc, int fr, int fq) const {
;     ...
;             for (int m = 0; m < 4; ++m) {
;                 const int row = row0 + ai * HALF + m * 16;
;                 const float r = __builtin_amdgcn_rsqf(rs[ai][m] * (1.0f / DM) + EPSN);
;                 const f32x4 g0 = acc[ai][0][m][0] * r, g1 = acc[ai][0][m][1] * r, u0 = acc[ai][1][m][0] * r, u1 = acc[ai][1][m][1] * r;
;                 u32x4 w;
;                 w.x = cvt_pk_bf16(silu_mul(g0[0], u0[0]), silu_mul(g0[1], u0[1])); w.y = cvt_pk_bf16(silu_mul(g0[2], u0[2]), silu_mul(g0[3], u0[3]));
;                 w.z = cvt_pk_bf16(silu_mul(g1[0], u1[0]), silu_mul(g1[1], u1[1])); w.w = cvt_pk_bf16(silu_mul(g1[2], u1[2]), silu_mul(g1[3], u1[3]));
;                 *(u32x4*)(act + (((size_t)u.pm * (DFF / 64) + (u.pn * 2 + (wc >> 1))) * 256 + (row - u.pm * BM)) * 64 + (wc & 1) * 32 + 8 * fq) = w;
	v_rsq_f32_e32 v96, v96
	s_nop 0
	v_pk_mul_f32 v[92:93], v[92:93], v[96:97] op_sel_hi:[1,0]
	v_pk_mul_f32 v[94:95], v[94:95], v[96:97] op_sel_hi:[1,0]
	v_pk_mul_f32 v[90:91], v[90:91], v[96:97] op_sel_hi:[1,0]
	v_pk_mul_f32 v[88:89], v[88:89], v[96:97] op_sel_hi:[1,0]
	v_pk_mul_f32 v[86:87], v[86:87], v[96:97] op_sel_hi:[1,0]
	v_pk_mul_f32 v[84:85], v[84:85], v[96:97] op_sel_hi:[1,0]
	v_pk_mul_f32 v[98:99], v[82:83], v[96:97] op_sel_hi:[1,0]
	v_pk_mul_f32 v[82:83], v[80:81], v[96:97] op_sel_hi:[1,0]
	v_pk_mul_f32 v[156:157], v[92:93], s[100:101]
	v_pk_mul_f32 v[158:159], v[94:95], s[100:101]
	v_exp_f32_e32 v156, v156
	v_exp_f32_e32 v157, v157
	v_exp_f32_e32 v158, v158
	v_exp_f32_e32 v159, v159
	v_pk_add_f32 v[156:157], v[156:157], 1.0 op_sel_hi:[1,0]
	v_pk_add_f32 v[158:159], v[158:159], 1.0 op_sel_hi:[1,0]
	v_rcp_f32_e32 v156, v156
	v_rcp_f32_e32 v157, v157
	v_rcp_f32_e32 v158, v158
	v_rcp_f32_e32 v159, v159
	v_pk_mul_f32 v[156:157], v[92:93], v[156:157]
	v_pk_mul_f32 v[158:159], v[94:95], v[158:159]
	v_pk_mul_f32 v[156:157], v[84:85], v[156:157]
	v_pk_mul_f32 v[158:159], v[86:87], v[158:159]
	v_pk_mul_f32 v[160:161], v[88:89], s[100:101]
	v_pk_mul_f32 v[162:163], v[90:91], s[100:101]
	v_exp_f32_e32 v160, v160
	v_exp_f32_e32 v161, v161
	v_exp_f32_e32 v162, v162
	v_exp_f32_e32 v163, v163
	v_pk_add_f32 v[160:161], v[160:161], 1.0 op_sel_hi:[1,0]
	v_pk_add_f32 v[162:163], v[162:163], 1.0 op_sel_hi:[1,0]
	v_rcp_f32_e32 v160, v160
	v_rcp_f32_e32 v161, v161
	v_rcp_f32_e32 v162, v162
	v_rcp_f32_e32 v163, v163
	v_pk_mul_f32 v[160:161], v[88:89], v[160:161]
	v_pk_mul_f32 v[162:163], v[90:91], v[162:163]
	v_pk_mul_f32 v[160:161], v[82:83], v[160:161]
	v_pk_mul_f32 v[162:163], v[98:99], v[162:163]
	v_cvt_pk_bf16_f32 v80, v156, v157
	v_cvt_pk_bf16_f32 v81, v158, v159
	v_cvt_pk_bf16_f32 v82, v160, v161
	v_cvt_pk_bf16_f32 v83, v162, v163
	global_store_dwordx4 v[164:165], v[80:83], off
	s_nop 1
	v_fmamk_f32 v80, v152, 0x3a000000, v143
	v_rsq_f32_e32 v80, v80
	s_nop 0
	v_pk_mul_f32 v[76:77], v[76:77], v[80:81] op_sel_hi:[1,0]
	v_pk_mul_f32 v[78:79], v[78:79], v[80:81] op_sel_hi:[1,0]
	v_pk_mul_f32 v[74:75], v[74:75], v[80:81] op_sel_hi:[1,0]
	v_pk_mul_f32 v[72:73], v[72:73], v[80:81] op_sel_hi:[1,0]
	v_pk_mul_f32 v[70:71], v[70:71], v[80:81] op_sel_hi:[1,0]
	v_pk_mul_f32 v[68:69], v[68:69], v[80:81] op_sel_hi:[1,0]
	v_pk_mul_f32 v[82:83], v[66:67], v[80:81] op_sel_hi:[1,0]
	v_pk_mul_f32 v[66:67], v[64:65], v[80:81] op_sel_hi:[1,0]
	v_pk_mul_f32 v[156:157], v[76:77], s[100:101]
	v_pk_mul_f32 v[158:159], v[78:79], s[100:101]
	v_exp_f32_e32 v156, v156
	v_exp_f32_e32 v157, v157
	v_exp_f32_e32 v158, v158
	v_exp_f32_e32 v159, v159
	v_pk_add_f32 v[156:157], v[156:157], 1.0 op_sel_hi:[1,0]
	v_pk_add_f32 v[158:159], v[158:159], 1.0 op_sel_hi:[1,0]
	v_rcp_f32_e32 v156, v156
	v_rcp_f32_e32 v157, v157
	v_rcp_f32_e32 v158, v158
	v_rcp_f32_e32 v159, v159
	v_pk_mul_f32 v[156:157], v[76:77], v[156:157]
	v_pk_mul_f32 v[158:159], v[78:79], v[158:159]
	v_pk_mul_f32 v[156:157], v[68:69], v[156:157]
	v_pk_mul_f32 v[158:159], v[70:71], v[158:159]
	v_pk_mul_f32 v[160:161], v[72:73], s[100:101]
	v_pk_mul_f32 v[162:163], v[74:75], s[100:101]
	v_exp_f32_e32 v160, v160
	v_exp_f32_e32 v161, v161
	v_exp_f32_e32 v162, v162
	v_exp_f32_e32 v163, v163
	v_pk_add_f32 v[160:161], v[160:161], 1.0 op_sel_hi:[1,0]
	v_pk_add_f32 v[162:163], v[162:163], 1.0 op_sel_hi:[1,0]
	v_rcp_f32_e32 v160, v160
	v_rcp_f32_e32 v161, v161
	v_rcp_f32_e32 v162, v162
	v_rcp_f32_e32 v163, v163
	v_pk_mul_f32 v[160:161], v[72:73], v[160:161]
	v_pk_mul_f32 v[162:163], v[74:75], v[162:163]
	v_pk_mul_f32 v[160:161], v[66:67], v[160:161]
	v_pk_mul_f32 v[162:163], v[82:83], v[162:163]
	v_cvt_pk_bf16_f32 v64, v156, v157
	v_cvt_pk_bf16_f32 v65, v158, v159
	v_cvt_pk_bf16_f32 v66, v160, v161
	v_cvt_pk_bf16_f32 v67, v162, v163
	global_store_dwordx4 v[164:165], v[64:67], off offset:2048
	s_nop 1
	v_fmamk_f32 v64, v153, 0x3a000000, v143
	v_rsq_f32_e32 v64, v64
	s_nop 0
	v_pk_mul_f32 v[60:61], v[60:61], v[64:65] op_sel_hi:[1,0]
	v_pk_mul_f32 v[62:63], v[62:63], v[64:65] op_sel_hi:[1,0]
	v_pk_mul_f32 v[58:59], v[58:59], v[64:65] op_sel_hi:[1,0]
	v_pk_mul_f32 v[56:57], v[56:57], v[64:65] op_sel_hi:[1,0]
	v_pk_mul_f32 v[54:55], v[54:55], v[64:65] op_sel_hi:[1,0]
	v_pk_mul_f32 v[52:53], v[52:53], v[64:65] op_sel_hi:[1,0]
	v_pk_mul_f32 v[66:67], v[50:51], v[64:65] op_sel_hi:[1,0]
	v_pk_mul_f32 v[50:51], v[48:49], v[64:65] op_sel_hi:[1,0]
	v_pk_mul_f32 v[156:157], v[60:61], s[100:101]
	v_pk_mul_f32 v[158:159], v[62:63], s[100:101]
	v_exp_f32_e32 v156, v156
	v_exp_f32_e32 v157, v157
	v_exp_f32_e32 v158, v158
	v_exp_f32_e32 v159, v159
	v_pk_add_f32 v[156:157], v[156:157], 1.0 op_sel_hi:[1,0]
	v_pk_add_f32 v[158:159], v[158:159], 1.0 op_sel_hi:[1,0]
	v_rcp_f32_e32 v156, v156
	v_rcp_f32_e32 v157, v157
	v_rcp_f32_e32 v158, v158
	v_rcp_f32_e32 v159, v159
	v_pk_mul_f32 v[156:157], v[60:61], v[156:157]
	v_pk_mul_f32 v[158:159], v[62:63], v[158:159]
	v_pk_mul_f32 v[156:157], v[52:53], v[156:157]
	v_pk_mul_f32 v[158:159], v[54:55], v[158:159]
	v_pk_mul_f32 v[160:161], v[56:57], s[100:101]
	v_pk_mul_f32 v[162:163], v[58:59], s[100:101]
	v_exp_f32_e32 v160, v160
	v_exp_f32_e32 v161, v161
	v_exp_f32_e32 v162, v162
	v_exp_f32_e32 v163, v163
	v_pk_add_f32 v[160:161], v[160:161], 1.0 op_sel_hi:[1,0]
	v_pk_add_f32 v[162:163], v[162:163], 1.0 op_sel_hi:[1,0]
	v_rcp_f32_e32 v160, v160
	v_rcp_f32_e32 v161, v161
	v_rcp_f32_e32 v162, v162
	v_rcp_f32_e32 v163, v163
	v_pk_mul_f32 v[160:161], v[56:57], v[160:161]
	v_pk_mul_f32 v[162:163], v[58:59], v[162:163]
	v_pk_mul_f32 v[160:161], v[50:51], v[160:161]
	v_pk_mul_f32 v[162:163], v[66:67], v[162:163]
; __device__ __forceinline__ unsigned cvt_pk_bf16(float lo, float hi) { unsigned r; asm volatile("v_cvt_pk_bf16_f32 %0, %1, %2" : "=v"(r) : "v"(lo), "v"(hi)); return r; }
; __device__ __forceinline__ float silu_mul(float g, float u) { return g * __builtin_amdgcn_rcpf(1.0f + __builtin_amdgcn_exp2f(-1.4426950408889634f * g)) * u; }
;     __device__ __forceinline__ void operator()(const f32x4 (&acc)[2][2][4][2], const Unit& u, int wr, int wc, int fr, int fq) const {
;     ...
;             for (int m = 0; m < 4; ++m) {
;                 const int row = row0 + ai * HALF + m * 16;
;                 const float r = __builtin_amdgcn_rsqf(rs[ai][m] * (1.0f / DM) + EPSN);
;                 const f32x4 g0 = acc[ai][0][m][0] * r, g1 = acc[ai][0][m][1] * r, u0 = acc[ai][1][m][0] * r, u1 = acc[ai][1][m][1] * r;
;                 u32x4 w;
;                 w.x = cvt_pk_bf16(silu_mul(g0[0], u0[0]), silu_mul(g0[1], u0[1])); w.y = cvt_pk_bf16(silu_mul(g0[2], u0[2]), silu_mul(g0[3], u0[3]));
;                 w.z = cvt_pk_bf16(silu_mul(g1[0], u1[0]), silu_mul(g1[1], u1[1])); w.w = cvt_pk_bf16(silu_mul(g1[2], u1[2]), silu_mul(g1[3], u1[3]));
;                 *(u32x4*)(act + (((size_t)u.pm * (DFF / 64) + (u.pn * 2 + (wc >> 1))) * 256 + (row - u.pm * BM)) * 64 + (wc & 1) * 32 + 8 * fq) = w;
	v_cvt_pk_bf16_f32 v48, v156, v157
	v_cvt_pk_bf16_f32 v49, v158, v159
	v_cvt_pk_bf16_f32 v50, v160, v161
	v_cvt_pk_bf16_f32 v51, v162, v163
	global_store_dwordx4 v[166:167], v[48:51], off offset:-4096
	s_nop 1
	v_fmamk_f32 v48, v144, 0x3a000000, v143
	v_rsq_f32_e32 v48, v48
	s_nop 0
	v_pk_mul_f32 v[44:45], v[44:45], v[48:49] op_sel_hi:[1,0]
	v_pk_mul_f32 v[46:47], v[46:47], v[48:49] op_sel_hi:[1,0]
	v_pk_mul_f32 v[42:43], v[42:43], v[48:49] op_sel_hi:[1,0]
	v_pk_mul_f32 v[40:41], v[40:41], v[48:49] op_sel_hi:[1,0]
	v_pk_mul_f32 v[38:39], v[38:39], v[48:49] op_sel_hi:[1,0]
	v_pk_mul_f32 v[36:37], v[36:37], v[48:49] op_sel_hi:[1,0]
	v_pk_mul_f32 v[50:51], v[34:35], v[48:49] op_sel_hi:[1,0]
	v_pk_mul_f32 v[34:35], v[32:33], v[48:49] op_sel_hi:[1,0]
	v_pk_mul_f32 v[156:157], v[44:45], s[100:101]
	v_pk_mul_f32 v[158:159], v[46:47], s[100:101]
	v_exp_f32_e32 v156, v156
	v_exp_f32_e32 v157, v157
	v_exp_f32_e32 v158, v158
	v_exp_f32_e32 v159, v159
	v_pk_add_f32 v[156:157], v[156:157], 1.0 op_sel_hi:[1,0]
	v_pk_add_f32 v[158:159], v[158:159], 1.0 op_sel_hi:[1,0]
	v_rcp_f32_e32 v156, v156
	v_rcp_f32_e32 v157, v157
	v_rcp_f32_e32 v158, v158
	v_rcp_f32_e32 v159, v159
	v_pk_mul_f32 v[156:157], v[44:45], v[156:157]
	v_pk_mul_f32 v[158:159], v[46:47], v[158:159]
	v_pk_mul_f32 v[156:157], v[36:37], v[156:157]
	v_pk_mul_f32 v[158:159], v[38:39], v[158:159]
	v_pk_mul_f32 v[160:161], v[40:41], s[100:101]
	v_pk_mul_f32 v[162:163], v[42:43], s[100:101]
	v_exp_f32_e32 v160, v160
	v_exp_f32_e32 v161, v161
	v_exp_f32_e32 v162, v162
	v_exp_f32_e32 v163, v163
	v_pk_add_f32 v[160:161], v[160:161], 1.0 op_sel_hi:[1,0]
	v_pk_add_f32 v[162:163], v[162:163], 1.0 op_sel_hi:[1,0]
	v_rcp_f32_e32 v160, v160
	v_rcp_f32_e32 v161, v161
	v_rcp_f32_e32 v162, v162
	v_rcp_f32_e32 v163, v163
	v_pk_mul_f32 v[160:161], v[40:41], v[160:161]
	v_pk_mul_f32 v[162:163], v[42:43], v[162:163]
	v_pk_mul_f32 v[160:161], v[34:35], v[160:161]
	v_pk_mul_f32 v[162:163], v[50:51], v[162:163]
	v_cvt_pk_bf16_f32 v32, v156, v157
	v_cvt_pk_bf16_f32 v33, v158, v159
	v_cvt_pk_bf16_f32 v34, v160, v161
	v_cvt_pk_bf16_f32 v35, v162, v163
	global_store_dwordx4 v[166:167], v[32:35], off offset:-2048
	s_nop 1
	v_fmamk_f32 v32, v139, 0x3a000000, v143
	v_rsq_f32_e32 v32, v32
	s_nop 0
	v_pk_mul_f32 v[28:29], v[28:29], v[32:33] op_sel_hi:[1,0]
	v_pk_mul_f32 v[30:31], v[30:31], v[32:33] op_sel_hi:[1,0]
	v_pk_mul_f32 v[26:27], v[26:27], v[32:33] op_sel_hi:[1,0]
	v_pk_mul_f32 v[24:25], v[24:25], v[32:33] op_sel_hi:[1,0]
	v_pk_mul_f32 v[22:23], v[22:23], v[32:33] op_sel_hi:[1,0]
	v_pk_mul_f32 v[20:21], v[20:21], v[32:33] op_sel_hi:[1,0]
	v_pk_mul_f32 v[34:35], v[18:19], v[32:33] op_sel_hi:[1,0]
	v_pk_mul_f32 v[18:19], v[16:17], v[32:33] op_sel_hi:[1,0]
	v_pk_mul_f32 v[156:157], v[28:29], s[100:101]
	v_pk_mul_f32 v[158:159], v[30:31], s[100:101]
	v_exp_f32_e32 v156, v156
	v_exp_f32_e32 v157, v157
	v_exp_f32_e32 v158, v158
	v_exp_f32_e32 v159, v159
	v_pk_add_f32 v[156:157], v[156:157], 1.0 op_sel_hi:[1,0]
	v_pk_add_f32 v[158:159], v[158:159], 1.0 op_sel_hi:[1,0]
	v_rcp_f32_e32 v156, v156
	v_rcp_f32_e32 v157, v157
	v_rcp_f32_e32 v158, v158
	v_rcp_f32_e32 v159, v159
	v_pk_mul_f32 v[156:157], v[28:29], v[156:157]
	v_pk_mul_f32 v[158:159], v[30:31], v[158:159]
	v_pk_mul_f32 v[156:157], v[20:21], v[156:157]
	v_pk_mul_f32 v[158:159], v[22:23], v[158:159]
	v_pk_mul_f32 v[160:161], v[24:25], s[100:101]
	v_pk_mul_f32 v[162:163], v[26:27], s[100:101]
	v_exp_f32_e32 v160, v160
	v_exp_f32_e32 v161, v161
	v_exp_f32_e32 v162, v162
	v_exp_f32_e32 v163, v163
	v_pk_add_f32 v[160:161], v[160:161], 1.0 op_sel_hi:[1,0]
	v_pk_add_f32 v[162:163], v[162:163], 1.0 op_sel_hi:[1,0]
	v_rcp_f32_e32 v160, v160
	v_rcp_f32_e32 v161, v161
	v_rcp_f32_e32 v162, v162
	v_rcp_f32_e32 v163, v163
	v_pk_mul_f32 v[160:161], v[24:25], v[160:161]
	v_pk_mul_f32 v[162:163], v[26:27], v[162:163]
	v_pk_mul_f32 v[160:161], v[18:19], v[160:161]
	v_pk_mul_f32 v[162:163], v[34:35], v[162:163]
	v_cvt_pk_bf16_f32 v16, v156, v157
	v_cvt_pk_bf16_f32 v17, v158, v159
	v_cvt_pk_bf16_f32 v18, v160, v161
	v_cvt_pk_bf16_f32 v19, v162, v163
	global_store_dwordx4 v[166:167], v[16:19], off
	s_nop 1
	v_fmamk_f32 v16, v137, 0x3a000000, v143
	v_rsq_f32_e32 v16, v16
	s_nop 0
	v_pk_mul_f32 v[12:13], v[12:13], v[16:17] op_sel_hi:[1,0]
	v_pk_mul_f32 v[14:15], v[14:15], v[16:17] op_sel_hi:[1,0]
	v_pk_mul_f32 v[10:11], v[10:11], v[16:17] op_sel_hi:[1,0]
	v_pk_mul_f32 v[8:9], v[8:9], v[16:17] op_sel_hi:[1,0]
	v_pk_mul_f32 v[6:7], v[6:7], v[16:17] op_sel_hi:[1,0]
	v_pk_mul_f32 v[4:5], v[4:5], v[16:17] op_sel_hi:[1,0]
	v_pk_mul_f32 v[18:19], v[2:3], v[16:17] op_sel_hi:[1,0]
	v_pk_mul_f32 v[2:3], v[0:1], v[16:17] op_sel_hi:[1,0]
	v_pk_mul_f32 v[156:157], v[12:13], s[100:101]
	v_pk_mul_f32 v[158:159], v[14:15], s[100:101]
	v_exp_f32_e32 v156, v156
	v_exp_f32_e32 v157, v157
	v_exp_f32_e32 v158, v158
	v_exp_f32_e32 v159, v159
	v_pk_add_f32 v[156:157], v[156:157], 1.0 op_sel_hi:[1,0]
	v_pk_add_f32 v[158:159], v[158:159], 1.0 op_sel_hi:[1,0]
	v_rcp_f32_e32 v156, v156
	v_rcp_f32_e32 v157, v157
	v_rcp_f32_e32 v158, v158
	v_rcp_f32_e32 v159, v159
	v_pk_mul_f32 v[156:157], v[12:13], v[156:157]
	v_pk_mul_f32 v[158:159], v[14:15], v[158:159]
	v_pk_mul_f32 v[156:157], v[4:5], v[156:157]
	v_pk_mul_f32 v[158:159], v[6:7], v[158:159]
	v_pk_mul_f32 v[160:161], v[8:9], s[100:101]
	v_pk_mul_f32 v[162:163], v[10:11], s[100:101]
	v_exp_f32_e32 v160, v160
	v_exp_f32_e32 v161, v161
	v_exp_f32_e32 v162, v162
	v_exp_f32_e32 v163, v163
	v_pk_add_f32 v[160:161], v[160:161], 1.0 op_sel_hi:[1,0]
	v_pk_add_f32 v[162:163], v[162:163], 1.0 op_sel_hi:[1,0]
	v_rcp_f32_e32 v160, v160
	v_rcp_f32_e32 v161, v161
	v_rcp_f32_e32 v162, v162
	v_rcp_f32_e32 v163, v163
	v_pk_mul_f32 v[160:161], v[8:9], v[160:161]
	v_pk_mul_f32 v[162:163], v[10:11], v[162:163]
	v_pk_mul_f32 v[160:161], v[2:3], v[160:161]
	v_pk_mul_f32 v[162:163], v[18:19], v[162:163]
	v_cvt_pk_bf16_f32 v0, v156, v157
	v_cvt_pk_bf16_f32 v1, v158, v159
	v_cvt_pk_bf16_f32 v2, v160, v161
	v_cvt_pk_bf16_f32 v3, v162, v163
	global_store_dwordx4 v[166:167], v[0:3], off offset:2048
	s_andn2_b64 vcc, exec, s[24:25]
	s_mov_b64 s[24:25], -1
	s_cbranch_vccnz .LBB0_1331
	s_andn2_b64 vcc, exec, s[0:1]
	s_cbranch_vccnz .LBB0_1330
	s_barrier
	s_branch .LBB0_1330
